# P12 ffn conv: nt streaming hint on the in-place g stores (loads already nt)
# baseline (speedup 1.0000x reference)
; __device__ __forceinline__ float sigm(float x) { return 1.f / (1.f + __expf(-x)); }
; __device__ __forceinline__ u32x4 pack8(const float (&f)[8]) { u32x4 w; w.x = pk2(f[0], f[1]); w.y = pk2(f[2], f[3]); w.z = pk2(f[4], f[5]); w.w = pk2(f[6], f[7]); return w; }
; __device__ __forceinline__ void ffn_conv_item(int tid_in, int b, int strip, bf16_t* h1, const bf16_t* h2, const float* cw, const float* cb, bool st = true) {
;     ...
;         for (int j = 0; j < 4; ++j) {
;             const size_t off = off0 + (size_t)(32 * blk + 8 * j + rl) * 5632;
;             const u32x4 cgv = cg4[j], cvv = cv4[j];
;             float xg[8], xv[8], yg[8], yv[8]; unpack8(cgv, xg); unpack8(cvv, xv);
; #pragma unroll
;             for (int e = 0; e < 8; ++e) { yg[e] = bg[e] + wg[2][e] * xg[e]; yv[e] = bv[e] + wv[2][e] * xv[e]; }
; #pragma unroll
;             for (int d = 1; d <= 2; ++d) {
;                 const bool own = (rl + d <= 7); const int src = (lane + 64 - 8 * d) & 63;
;                 const u32x4 sg = own ? cgv : pg, sv = own ? cvv : pv;
;                 u32x4 g, v; g.x = __shfl(sg.x, src); g.y = __shfl(sg.y, src); g.z = __shfl(sg.z, src); g.w = __shfl(sg.w, src);
;                 v.x = __shfl(sv.x, src); v.y = __shfl(sv.y, src); v.z = __shfl(sv.z, src); v.w = __shfl(sv.w, src);
;                 float dg[8], dv[8]; unpack8(g, dg); unpack8(v, dv);
; #pragma unroll
;                 for (int e = 0; e < 8; ++e) { yg[e] += wg[2 - d][e] * dg[e]; yv[e] += wv[2 - d][e] * dv[e]; }
;             }
; #pragma unroll
;             for (int e = 0; e < 8; ++e) yg[e] = yg[e] * sigm(yg[e]) * yv[e];
;             { const u32x4 o_ = pack8(yg); if (st) *(u32x4*)(h1 + off) = o_; else asm volatile("" :: "v"(o_)); }
;             pg = cgv; pv = cvv;
.LBB0_24:
	v_cndmask_b32_e64 v142, v97, v105, s[40:41]
	v_cndmask_b32_e64 v145, v94, v102, s[40:41]
	v_cndmask_b32_e64 v151, v98, v90, s[40:41]
	v_cndmask_b32_e64 v143, v96, v104, s[40:41]
	ds_bpermute_b32 v145, v0, v145
	ds_bpermute_b32 v154, v0, v142
	ds_bpermute_b32 v142, v0, v151
	v_cndmask_b32_e64 v104, v104, v96, s[42:43]
	v_cndmask_b32_e64 v102, v102, v94, s[42:43]
	v_cndmask_b32_e64 v90, v90, v98, s[42:43]
	ds_bpermute_b32 v102, v147, v102
	ds_bpermute_b32 v157, v147, v104
	ds_bpermute_b32 v104, v147, v90
	v_cndmask_b32_e64 v150, v99, v91, s[40:41]
	v_cndmask_b32_e64 v105, v105, v97, s[42:43]
	v_cndmask_b32_e64 v91, v91, v99, s[42:43]
	v_cndmask_b32_e64 v148, v101, v93, s[40:41]
	v_cndmask_b32_e64 v149, v100, v92, s[40:41]
	v_cndmask_b32_e64 v93, v93, v101, s[42:43]
	v_cndmask_b32_e64 v92, v92, v100, s[42:43]
	ds_bpermute_b32 v158, v147, v105
	ds_bpermute_b32 v105, v147, v91
	v_lshlrev_b32_e32 v91, 16, v94
	v_lshlrev_b32_e32 v90, 16, v98
	v_cndmask_b32_e64 v144, v95, v103, s[40:41]
	ds_bpermute_b32 v159, v147, v92
	ds_bpermute_b32 v160, v147, v93
	v_pk_fma_f32 v[90:91], v[132:133], v[90:91], v[130:131]
	s_waitcnt lgkmcnt(9)
	v_lshlrev_b32_e32 v93, 16, v145
	s_waitcnt lgkmcnt(7)
	v_lshlrev_b32_e32 v92, 16, v142
	ds_bpermute_b32 v152, v0, v144
	ds_bpermute_b32 v153, v0, v143
	ds_bpermute_b32 v143, v0, v150
	v_cndmask_b32_e64 v103, v103, v95, s[42:43]
	v_pk_fma_f32 v[90:91], v[134:135], v[92:93], v[90:91]
	s_waitcnt lgkmcnt(9)
	v_lshlrev_b32_e32 v93, 16, v102
	s_waitcnt lgkmcnt(7)
	v_lshlrev_b32_e32 v92, 16, v104
	ds_bpermute_b32 v155, v0, v149
	ds_bpermute_b32 v156, v0, v148
	ds_bpermute_b32 v103, v147, v103
	v_pk_fma_f32 v[148:149], v[136:137], v[92:93], v[90:91]
	v_and_b32_e32 v91, 0xffff0000, v94
	v_and_b32_e32 v90, 0xffff0000, v98
	v_pk_fma_f32 v[90:91], v[22:23], v[90:91], v[30:31]
	v_and_b32_e32 v93, 0xffff0000, v145
	v_and_b32_e32 v92, 0xffff0000, v142
	v_pk_fma_f32 v[90:91], v[14:15], v[92:93], v[90:91]
	v_and_b32_e32 v93, 0xffff0000, v102
	v_and_b32_e32 v92, 0xffff0000, v104
	v_pk_fma_f32 v[150:151], v[6:7], v[92:93], v[90:91]
	v_lshlrev_b32_e32 v91, 16, v95
	v_lshlrev_b32_e32 v90, 16, v99
	v_pk_fma_f32 v[90:91], v[124:125], v[90:91], v[122:123]
	s_waitcnt lgkmcnt(5)
	v_lshlrev_b32_e32 v93, 16, v152
	s_waitcnt lgkmcnt(3)
	v_lshlrev_b32_e32 v92, 16, v143
	v_pk_fma_f32 v[90:91], v[126:127], v[92:93], v[90:91]
	s_waitcnt lgkmcnt(0)
	v_lshlrev_b32_e32 v93, 16, v103
	v_lshlrev_b32_e32 v92, 16, v105
	v_pk_fma_f32 v[144:145], v[128:129], v[92:93], v[90:91]
	v_and_b32_e32 v91, 0xffff0000, v95
	v_and_b32_e32 v90, 0xffff0000, v99
	v_pk_fma_f32 v[90:91], v[24:25], v[90:91], v[32:33]
	v_and_b32_e32 v93, 0xffff0000, v152
	v_and_b32_e32 v92, 0xffff0000, v143
	v_pk_fma_f32 v[90:91], v[16:17], v[92:93], v[90:91]
	v_and_b32_e32 v93, 0xffff0000, v103
	v_and_b32_e32 v92, 0xffff0000, v105
	v_pk_fma_f32 v[142:143], v[8:9], v[92:93], v[90:91]
	v_lshlrev_b32_e32 v91, 16, v96
	v_lshlrev_b32_e32 v90, 16, v100
	v_pk_fma_f32 v[90:91], v[116:117], v[90:91], v[114:115]
	v_lshlrev_b32_e32 v93, 16, v153
	v_lshlrev_b32_e32 v92, 16, v155
	v_pk_fma_f32 v[90:91], v[118:119], v[92:93], v[90:91]
	v_lshlrev_b32_e32 v93, 16, v157
	v_lshlrev_b32_e32 v92, 16, v159
	v_pk_fma_f32 v[104:105], v[120:121], v[92:93], v[90:91]
	v_and_b32_e32 v91, 0xffff0000, v96
	v_and_b32_e32 v90, 0xffff0000, v100
	v_pk_fma_f32 v[90:91], v[18:19], v[90:91], v[26:27]
	v_and_b32_e32 v93, 0xffff0000, v153
	v_and_b32_e32 v92, 0xffff0000, v155
	v_pk_fma_f32 v[90:91], v[10:11], v[92:93], v[90:91]
	v_and_b32_e32 v93, 0xffff0000, v157
	v_and_b32_e32 v92, 0xffff0000, v159
	v_pk_fma_f32 v[102:103], v[2:3], v[92:93], v[90:91]
	v_lshlrev_b32_e32 v91, 16, v97
	v_lshlrev_b32_e32 v90, 16, v101
	v_pk_fma_f32 v[90:91], v[108:109], v[90:91], v[106:107]
	v_lshlrev_b32_e32 v93, 16, v154
	v_lshlrev_b32_e32 v92, 16, v156
	v_pk_fma_f32 v[90:91], v[110:111], v[92:93], v[90:91]
	v_lshlrev_b32_e32 v93, 16, v158
	v_lshlrev_b32_e32 v92, 16, v160
	v_pk_fma_f32 v[92:93], v[112:113], v[92:93], v[90:91]
	v_and_b32_e32 v91, 0xffff0000, v97
	v_and_b32_e32 v90, 0xffff0000, v101
	v_pk_fma_f32 v[90:91], v[20:21], v[90:91], v[28:29]
	v_and_b32_e32 v153, 0xffff0000, v154
	v_and_b32_e32 v152, 0xffff0000, v156
	v_pk_fma_f32 v[90:91], v[12:13], v[152:153], v[90:91]
	v_and_b32_e32 v153, 0xffff0000, v158
	v_and_b32_e32 v152, 0xffff0000, v160
	v_pk_fma_f32 v[90:91], v[4:5], v[152:153], v[90:91]
	v_mul_f32_e32 v152, 0xbfb8aa3b, v149
	v_exp_f32_e32 v152, v152
	s_mov_b32 s9, 0x4a00000
	s_add_u32 s34, s34, 0x58000
	s_addc_u32 s35, s35, 0
	v_add_f32_e32 v152, 1.0, v152
	s_cmp_lg_u32 s34, 0x580000
	v_rcp_f32_e32 v152, v152
	s_nop 0
	v_mul_f32_e32 v149, v149, v152
	v_mul_f32_e32 v148, v148, v149
	v_mul_f32_e32 v149, 0xbfb8aa3b, v151
	v_exp_f32_e32 v149, v149
	s_nop 0
	v_add_f32_e32 v149, 1.0, v149
	s_nop 0
	v_rcp_f32_e32 v149, v149
	s_nop 0
	v_mul_f32_e32 v149, v151, v149
	v_mul_f32_e32 v149, v150, v149
	v_mul_f32_e32 v150, 0xbfb8aa3b, v145
	v_exp_f32_e32 v150, v150
	s_nop 0
	v_add_f32_e32 v150, 1.0, v150
	s_nop 0
	v_rcp_f32_e32 v150, v150
	s_nop 0
	v_mul_f32_e32 v145, v145, v150
	v_mul_f32_e32 v144, v144, v145
	v_mul_f32_e32 v145, 0xbfb8aa3b, v143
	v_exp_f32_e32 v145, v145
	s_nop 0
	v_add_f32_e32 v145, 1.0, v145
	s_nop 0
	v_rcp_f32_e32 v145, v145
	s_nop 0
	v_mul_f32_e32 v143, v143, v145
	v_mul_f32_e32 v142, v142, v143
	v_mul_f32_e32 v143, 0xbfb8aa3b, v105
	v_exp_f32_e32 v143, v143
	s_nop 0
	v_add_f32_e32 v143, 1.0, v143
	s_nop 0
	v_rcp_f32_e32 v143, v143
	s_nop 0
	v_mul_f32_e32 v105, v105, v143
	v_mul_f32_e32 v104, v104, v105
	v_mul_f32_e32 v105, 0xbfb8aa3b, v103
	v_exp_f32_e32 v105, v105
	s_nop 0
	v_add_f32_e32 v105, 1.0, v105
; __device__ __forceinline__ float sigm(float x) { return 1.f / (1.f + __expf(-x)); }
; __device__ __forceinline__ u32x4 pack8(const float (&f)[8]) { u32x4 w; w.x = pk2(f[0], f[1]); w.y = pk2(f[2], f[3]); w.z = pk2(f[4], f[5]); w.w = pk2(f[6], f[7]); return w; }
; __device__ __forceinline__ void ffn_conv_item(int tid_in, int b, int strip, bf16_t* h1, const bf16_t* h2, const float* cw, const float* cb, bool st = true) {
;     ...
;         for (int j = 0; j < 4; ++j) {
;             const size_t off = off0 + (size_t)(32 * blk + 8 * j + rl) * 5632;
;             const u32x4 cgv = cg4[j], cvv = cv4[j];
;             float xg[8], xv[8], yg[8], yv[8]; unpack8(cgv, xg); unpack8(cvv, xv);
; #pragma unroll
;             for (int e = 0; e < 8; ++e) { yg[e] = bg[e] + wg[2][e] * xg[e]; yv[e] = bv[e] + wv[2][e] * xv[e]; }
; #pragma unroll
;             for (int d = 1; d <= 2; ++d) {
;                 const bool own = (rl + d <= 7); const int src = (lane + 64 - 8 * d) & 63;
;                 const u32x4 sg = own ? cgv : pg, sv = own ? cvv : pv;
;                 u32x4 g, v; g.x = __shfl(sg.x, src); g.y = __shfl(sg.y, src); g.z = __shfl(sg.z, src); g.w = __shfl(sg.w, src);
;                 v.x = __shfl(sv.x, src); v.y = __shfl(sv.y, src); v.z = __shfl(sv.z, src); v.w = __shfl(sv.w, src);
;                 float dg[8], dv[8]; unpack8(g, dg); unpack8(v, dv);
; #pragma unroll
;                 for (int e = 0; e < 8; ++e) { yg[e] += wg[2 - d][e] * dg[e]; yv[e] += wv[2 - d][e] * dv[e]; }
;             }
; #pragma unroll
;             for (int e = 0; e < 8; ++e) yg[e] = yg[e] * sigm(yg[e]) * yv[e];
;             { const u32x4 o_ = pack8(yg); if (st) *(u32x4*)(h1 + off) = o_; else asm volatile("" :: "v"(o_)); }
;             pg = cgv; pv = cvv;
	s_nop 0
	v_rcp_f32_e32 v105, v105
	s_nop 0
	v_mul_f32_e32 v103, v103, v105
	v_mul_f32_e32 v102, v102, v103
	v_mul_f32_e32 v103, 0xbfb8aa3b, v93
	v_exp_f32_e32 v103, v103
	s_nop 0
	v_add_f32_e32 v103, 1.0, v103
	s_nop 0
	v_rcp_f32_e32 v103, v103
	s_nop 0
	v_mul_f32_e32 v93, v93, v103
	v_mul_f32_e32 v93, v92, v93
	v_mul_f32_e32 v92, 0xbfb8aa3b, v91
	v_exp_f32_e32 v92, v92
	s_nop 0
	v_add_f32_e32 v92, 1.0, v92
	s_nop 0
	v_rcp_f32_e32 v92, v92
	s_nop 0
	v_mul_f32_e32 v91, v91, v92
	v_mul_f32_e32 v103, v90, v91
	v_cvt_pk_bf16_f32 v90, v148, v149
	v_cvt_pk_bf16_f32 v91, v144, v142
	v_cvt_pk_bf16_f32 v92, v104, v102
	v_add_co_u32_e32 v102, vcc, s9, v140
	v_cvt_pk_bf16_f32 v93, v93, v103
	v_cndmask_b32_e64 v105, v86, v98, s[40:41]
	s_nop 0
	v_addc_co_u32_e32 v103, vcc, 0, v141, vcc
	global_store_dwordx4 v[102:103], v[90:93], off nt
	ds_bpermute_b32 v105, v0, v105
	v_cndmask_b32_e64 v104, v87, v99, s[40:41]
	v_cndmask_b32_e64 v90, v85, v97, s[40:41]
	v_cndmask_b32_e64 v93, v82, v94, s[40:41]
	ds_bpermute_b32 v142, v0, v93
	ds_bpermute_b32 v145, v0, v90
	v_cndmask_b32_e64 v90, v97, v85, s[42:43]
	v_cndmask_b32_e64 v93, v94, v82, s[42:43]
	v_cndmask_b32_e64 v97, v98, v86, s[42:43]
	ds_bpermute_b32 v98, v147, v93
	ds_bpermute_b32 v97, v147, v97
	v_cndmask_b32_e64 v91, v84, v96, s[40:41]
	v_cndmask_b32_e64 v92, v83, v95, s[40:41]
	ds_bpermute_b32 v144, v0, v91
	v_cndmask_b32_e64 v91, v96, v84, s[42:43]
	ds_bpermute_b32 v143, v0, v92
	v_cndmask_b32_e64 v92, v95, v83, s[42:43]
	ds_bpermute_b32 v151, v147, v91
	ds_bpermute_b32 v152, v147, v90
	v_lshlrev_b32_e32 v91, 16, v82
	v_lshlrev_b32_e32 v90, 16, v86
	v_cndmask_b32_e64 v96, v99, v87, s[42:43]
	ds_bpermute_b32 v99, v147, v92
	v_pk_fma_f32 v[90:91], v[132:133], v[90:91], v[130:131]
	s_waitcnt lgkmcnt(8)
	v_lshlrev_b32_e32 v93, 16, v142
	v_lshlrev_b32_e32 v92, 16, v105
	v_cndmask_b32_e64 v102, v89, v101, s[40:41]
	v_cndmask_b32_e64 v103, v88, v100, s[40:41]
	ds_bpermute_b32 v148, v0, v104
	v_pk_fma_f32 v[90:91], v[134:135], v[92:93], v[90:91]
	s_waitcnt lgkmcnt(7)
	v_lshlrev_b32_e32 v93, 16, v98
	s_waitcnt lgkmcnt(6)
	v_lshlrev_b32_e32 v92, 16, v97
	ds_bpermute_b32 v149, v0, v103
	ds_bpermute_b32 v150, v0, v102
	ds_bpermute_b32 v96, v147, v96
	v_pk_fma_f32 v[102:103], v[136:137], v[92:93], v[90:91]
	v_and_b32_e32 v91, 0xffff0000, v82
	v_and_b32_e32 v90, 0xffff0000, v86
	v_pk_fma_f32 v[90:91], v[22:23], v[90:91], v[30:31]
	v_and_b32_e32 v93, 0xffff0000, v142
	v_and_b32_e32 v92, 0xffff0000, v105
	v_pk_fma_f32 v[90:91], v[14:15], v[92:93], v[90:91]
	v_and_b32_e32 v93, 0xffff0000, v98
	v_and_b32_e32 v92, 0xffff0000, v97
	v_pk_fma_f32 v[104:105], v[6:7], v[92:93], v[90:91]
	v_lshlrev_b32_e32 v91, 16, v83
	v_lshlrev_b32_e32 v90, 16, v87
	v_pk_fma_f32 v[90:91], v[124:125], v[90:91], v[122:123]
	s_waitcnt lgkmcnt(7)
	v_lshlrev_b32_e32 v93, 16, v143
	s_waitcnt lgkmcnt(3)
	v_lshlrev_b32_e32 v92, 16, v148
	v_cndmask_b32_e64 v95, v100, v88, s[42:43]
	v_pk_fma_f32 v[90:91], v[126:127], v[92:93], v[90:91]
	v_lshlrev_b32_e32 v93, 16, v99
	s_waitcnt lgkmcnt(0)
	v_lshlrev_b32_e32 v92, 16, v96
	v_cndmask_b32_e64 v94, v101, v89, s[42:43]
	ds_bpermute_b32 v95, v147, v95
	v_pk_fma_f32 v[100:101], v[128:129], v[92:93], v[90:91]
	v_and_b32_e32 v91, 0xffff0000, v83
	v_and_b32_e32 v90, 0xffff0000, v87
	v_pk_fma_f32 v[90:91], v[24:25], v[90:91], v[32:33]
	v_and_b32_e32 v93, 0xffff0000, v143
	v_and_b32_e32 v92, 0xffff0000, v148
	v_pk_fma_f32 v[90:91], v[16:17], v[92:93], v[90:91]
	v_and_b32_e32 v93, 0xffff0000, v99
	v_and_b32_e32 v92, 0xffff0000, v96
	v_pk_fma_f32 v[98:99], v[8:9], v[92:93], v[90:91]
	v_lshlrev_b32_e32 v91, 16, v84
	v_lshlrev_b32_e32 v90, 16, v88
	v_pk_fma_f32 v[90:91], v[116:117], v[90:91], v[114:115]
	v_lshlrev_b32_e32 v93, 16, v144
	v_lshlrev_b32_e32 v92, 16, v149
	v_pk_fma_f32 v[90:91], v[118:119], v[92:93], v[90:91]
	v_lshlrev_b32_e32 v93, 16, v151
	s_waitcnt lgkmcnt(0)
	v_lshlrev_b32_e32 v92, 16, v95
	ds_bpermute_b32 v153, v147, v94
	v_pk_fma_f32 v[96:97], v[120:121], v[92:93], v[90:91]
	v_and_b32_e32 v91, 0xffff0000, v84
	v_and_b32_e32 v90, 0xffff0000, v88
	v_pk_fma_f32 v[90:91], v[18:19], v[90:91], v[26:27]
	v_and_b32_e32 v93, 0xffff0000, v144
	v_and_b32_e32 v92, 0xffff0000, v149
	v_pk_fma_f32 v[90:91], v[10:11], v[92:93], v[90:91]
	v_and_b32_e32 v93, 0xffff0000, v151
	v_and_b32_e32 v92, 0xffff0000, v95
	v_pk_fma_f32 v[94:95], v[2:3], v[92:93], v[90:91]
	v_lshlrev_b32_e32 v91, 16, v85
	v_lshlrev_b32_e32 v90, 16, v89
	v_pk_fma_f32 v[90:91], v[108:109], v[90:91], v[106:107]
	v_lshlrev_b32_e32 v93, 16, v145
	v_lshlrev_b32_e32 v92, 16, v150
	v_pk_fma_f32 v[90:91], v[110:111], v[92:93], v[90:91]
	v_lshlrev_b32_e32 v93, 16, v152
	s_waitcnt lgkmcnt(0)
; __device__ __forceinline__ float sigm(float x) { return 1.f / (1.f + __expf(-x)); }
; __device__ __forceinline__ u32x4 pack8(const float (&f)[8]) { u32x4 w; w.x = pk2(f[0], f[1]); w.y = pk2(f[2], f[3]); w.z = pk2(f[4], f[5]); w.w = pk2(f[6], f[7]); return w; }
; __device__ __forceinline__ void ffn_conv_item(int tid_in, int b, int strip, bf16_t* h1, const bf16_t* h2, const float* cw, const float* cb, bool st = true) {
;     ...
;         for (int j = 0; j < 4; ++j) {
;             const size_t off = off0 + (size_t)(32 * blk + 8 * j + rl) * 5632;
;             const u32x4 cgv = cg4[j], cvv = cv4[j];
;             float xg[8], xv[8], yg[8], yv[8]; unpack8(cgv, xg); unpack8(cvv, xv);
; #pragma unroll
;             for (int e = 0; e < 8; ++e) { yg[e] = bg[e] + wg[2][e] * xg[e]; yv[e] = bv[e] + wv[2][e] * xv[e]; }
; #pragma unroll
;             for (int d = 1; d <= 2; ++d) {
;                 const bool own = (rl + d <= 7); const int src = (lane + 64 - 8 * d) & 63;
;                 const u32x4 sg = own ? cgv : pg, sv = own ? cvv : pv;
;                 u32x4 g, v; g.x = __shfl(sg.x, src); g.y = __shfl(sg.y, src); g.z = __shfl(sg.z, src); g.w = __shfl(sg.w, src);
;                 v.x = __shfl(sv.x, src); v.y = __shfl(sv.y, src); v.z = __shfl(sv.z, src); v.w = __shfl(sv.w, src);
;                 float dg[8], dv[8]; unpack8(g, dg); unpack8(v, dv);
; #pragma unroll
;                 for (int e = 0; e < 8; ++e) { yg[e] += wg[2 - d][e] * dg[e]; yv[e] += wv[2 - d][e] * dv[e]; }
;             }
; #pragma unroll
;             for (int e = 0; e < 8; ++e) yg[e] = yg[e] * sigm(yg[e]) * yv[e];
;             { const u32x4 o_ = pack8(yg); if (st) *(u32x4*)(h1 + off) = o_; else asm volatile("" :: "v"(o_)); }
;             pg = cgv; pv = cvv;
	v_lshlrev_b32_e32 v92, 16, v153
	v_pk_fma_f32 v[92:93], v[112:113], v[92:93], v[90:91]
	v_and_b32_e32 v91, 0xffff0000, v85
	v_and_b32_e32 v90, 0xffff0000, v89
	v_pk_fma_f32 v[90:91], v[20:21], v[90:91], v[28:29]
	v_and_b32_e32 v143, 0xffff0000, v145
	v_and_b32_e32 v142, 0xffff0000, v150
	v_pk_fma_f32 v[90:91], v[12:13], v[142:143], v[90:91]
	v_and_b32_e32 v143, 0xffff0000, v152
	v_and_b32_e32 v142, 0xffff0000, v153
	v_pk_fma_f32 v[90:91], v[4:5], v[142:143], v[90:91]
	v_mul_f32_e32 v142, 0xbfb8aa3b, v103
	v_exp_f32_e32 v142, v142
	s_mov_b32 s9, 0x4a16000
	v_add_f32_e32 v142, 1.0, v142
	s_nop 0
	v_rcp_f32_e32 v142, v142
	s_nop 0
	v_mul_f32_e32 v103, v103, v142
	v_mul_f32_e32 v102, v102, v103
	v_mul_f32_e32 v103, 0xbfb8aa3b, v105
	v_exp_f32_e32 v103, v103
	s_nop 0
	v_add_f32_e32 v103, 1.0, v103
	s_nop 0
	v_rcp_f32_e32 v103, v103
	s_nop 0
	v_mul_f32_e32 v103, v105, v103
	v_mul_f32_e32 v103, v104, v103
	v_mul_f32_e32 v104, 0xbfb8aa3b, v101
	v_exp_f32_e32 v104, v104
	s_nop 0
	v_add_f32_e32 v104, 1.0, v104
	s_nop 0
	v_rcp_f32_e32 v104, v104
	s_nop 0
	v_mul_f32_e32 v101, v101, v104
	v_mul_f32_e32 v100, v100, v101
	v_mul_f32_e32 v101, 0xbfb8aa3b, v99
	v_exp_f32_e32 v101, v101
	s_nop 0
	v_add_f32_e32 v101, 1.0, v101
	s_nop 0
	v_rcp_f32_e32 v101, v101
	s_nop 0
	v_mul_f32_e32 v99, v99, v101
	v_mul_f32_e32 v98, v98, v99
	v_mul_f32_e32 v99, 0xbfb8aa3b, v97
	v_exp_f32_e32 v99, v99
	s_nop 0
	v_add_f32_e32 v99, 1.0, v99
	s_nop 0
	v_rcp_f32_e32 v99, v99
	s_nop 0
	v_mul_f32_e32 v97, v97, v99
	v_mul_f32_e32 v96, v96, v97
	v_mul_f32_e32 v97, 0xbfb8aa3b, v95
	v_exp_f32_e32 v97, v97
	s_nop 0
	v_add_f32_e32 v97, 1.0, v97
	s_nop 0
	v_rcp_f32_e32 v97, v97
	s_nop 0
	v_mul_f32_e32 v95, v95, v97
	v_mul_f32_e32 v94, v94, v95
	v_mul_f32_e32 v95, 0xbfb8aa3b, v93
	v_exp_f32_e32 v95, v95
	s_nop 0
	v_add_f32_e32 v95, 1.0, v95
	s_nop 0
	v_rcp_f32_e32 v95, v95
	s_nop 0
	v_mul_f32_e32 v93, v93, v95
	v_mul_f32_e32 v93, v92, v93
	v_mul_f32_e32 v92, 0xbfb8aa3b, v91
	v_exp_f32_e32 v92, v92
	s_nop 0
	v_add_f32_e32 v92, 1.0, v92
	s_nop 0
	v_rcp_f32_e32 v92, v92
	s_nop 0
	v_mul_f32_e32 v91, v91, v92
	v_mul_f32_e32 v95, v90, v91
	v_cvt_pk_bf16_f32 v90, v102, v103
	v_cvt_pk_bf16_f32 v91, v100, v98
	v_cvt_pk_bf16_f32 v92, v96, v94
	v_add_co_u32_e32 v94, vcc, s9, v140
	v_cvt_pk_bf16_f32 v93, v93, v95
	v_cndmask_b32_e64 v97, v78, v86, s[40:41]
	s_nop 0
	v_addc_co_u32_e32 v95, vcc, 0, v141, vcc
	global_store_dwordx4 v[94:95], v[90:93], off nt
	v_cndmask_b32_e64 v86, v86, v78, s[42:43]
	ds_bpermute_b32 v86, v147, v86
	v_cndmask_b32_e64 v90, v77, v85, s[40:41]
	v_cndmask_b32_e64 v93, v74, v82, s[40:41]
	v_cndmask_b32_e64 v92, v75, v83, s[40:41]
	ds_bpermute_b32 v93, v0, v93
	ds_bpermute_b32 v100, v0, v90
	ds_bpermute_b32 v90, v0, v97
	v_cndmask_b32_e64 v82, v82, v74, s[42:43]
	ds_bpermute_b32 v98, v0, v92
	ds_bpermute_b32 v92, v147, v82
	v_cndmask_b32_e64 v83, v83, v75, s[42:43]
	v_cndmask_b32_e64 v91, v76, v84, s[40:41]
	v_cndmask_b32_e64 v85, v85, v77, s[42:43]
	v_cndmask_b32_e64 v84, v84, v76, s[42:43]
	ds_bpermute_b32 v103, v147, v83
	v_lshlrev_b32_e32 v83, 16, v74
	v_lshlrev_b32_e32 v82, 16, v78
	v_cndmask_b32_e64 v96, v79, v87, s[40:41]
	ds_bpermute_b32 v104, v147, v84
	ds_bpermute_b32 v105, v147, v85
	v_pk_fma_f32 v[82:83], v[132:133], v[82:83], v[130:131]
	s_waitcnt lgkmcnt(7)
	v_lshlrev_b32_e32 v85, 16, v93
	s_waitcnt lgkmcnt(5)
	v_lshlrev_b32_e32 v84, 16, v90
	v_cndmask_b32_e64 v94, v81, v89, s[40:41]
	v_cndmask_b32_e64 v95, v80, v88, s[40:41]
	ds_bpermute_b32 v99, v0, v91
	ds_bpermute_b32 v91, v0, v96
	v_cndmask_b32_e64 v87, v87, v79, s[42:43]
	v_pk_fma_f32 v[82:83], v[134:135], v[84:85], v[82:83]
	s_waitcnt lgkmcnt(5)
	v_lshlrev_b32_e32 v85, 16, v92
	v_lshlrev_b32_e32 v84, 16, v86
	ds_bpermute_b32 v101, v0, v95
	ds_bpermute_b32 v102, v0, v94
	ds_bpermute_b32 v87, v147, v87
	v_pk_fma_f32 v[94:95], v[136:137], v[84:85], v[82:83]
	v_and_b32_e32 v83, 0xffff0000, v74
	v_and_b32_e32 v82, 0xffff0000, v78
	v_pk_fma_f32 v[82:83], v[22:23], v[82:83], v[30:31]
	v_and_b32_e32 v85, 0xffff0000, v93
	v_and_b32_e32 v84, 0xffff0000, v90
	v_pk_fma_f32 v[82:83], v[14:15], v[84:85], v[82:83]
	v_and_b32_e32 v85, 0xffff0000, v92
	v_and_b32_e32 v84, 0xffff0000, v86
	v_pk_fma_f32 v[96:97], v[6:7], v[84:85], v[82:83]
	v_lshlrev_b32_e32 v83, 16, v75
	v_lshlrev_b32_e32 v82, 16, v79
	v_pk_fma_f32 v[82:83], v[124:125], v[82:83], v[122:123]
	v_lshlrev_b32_e32 v85, 16, v98
	s_waitcnt lgkmcnt(3)
	v_lshlrev_b32_e32 v84, 16, v91
	v_cndmask_b32_e64 v88, v88, v80, s[42:43]
	v_pk_fma_f32 v[82:83], v[126:127], v[84:85], v[82:83]
	v_lshlrev_b32_e32 v85, 16, v103
	s_waitcnt lgkmcnt(0)
	v_lshlrev_b32_e32 v84, 16, v87
	ds_bpermute_b32 v142, v147, v88
	v_pk_fma_f32 v[92:93], v[128:129], v[84:85], v[82:83]
	v_and_b32_e32 v83, 0xffff0000, v75
	v_and_b32_e32 v82, 0xffff0000, v79
	v_pk_fma_f32 v[82:83], v[24:25], v[82:83], v[32:33]
	v_and_b32_e32 v85, 0xffff0000, v98
	v_and_b32_e32 v84, 0xffff0000, v91
	v_pk_fma_f32 v[82:83], v[16:17], v[84:85], v[82:83]
	v_and_b32_e32 v85, 0xffff0000, v103
	v_and_b32_e32 v84, 0xffff0000, v87
	v_pk_fma_f32 v[90:91], v[8:9], v[84:85], v[82:83]
	v_lshlrev_b32_e32 v83, 16, v76
	v_lshlrev_b32_e32 v82, 16, v80
	v_pk_fma_f32 v[82:83], v[116:117], v[82:83], v[114:115]
	v_lshlrev_b32_e32 v85, 16, v99
	v_lshlrev_b32_e32 v84, 16, v101
	v_cndmask_b32_e64 v89, v89, v81, s[42:43]
	v_pk_fma_f32 v[82:83], v[118:119], v[84:85], v[82:83]
	v_lshlrev_b32_e32 v85, 16, v104
	s_waitcnt lgkmcnt(0)
; __device__ __forceinline__ float sigm(float x) { return 1.f / (1.f + __expf(-x)); }
; __device__ __forceinline__ u32x4 pack8(const float (&f)[8]) { u32x4 w; w.x = pk2(f[0], f[1]); w.y = pk2(f[2], f[3]); w.z = pk2(f[4], f[5]); w.w = pk2(f[6], f[7]); return w; }
; __device__ __forceinline__ void ffn_conv_item(int tid_in, int b, int strip, bf16_t* h1, const bf16_t* h2, const float* cw, const float* cb, bool st = true) {
;     ...
;         for (int j = 0; j < 4; ++j) {
;             const size_t off = off0 + (size_t)(32 * blk + 8 * j + rl) * 5632;
;             const u32x4 cgv = cg4[j], cvv = cv4[j];
;             float xg[8], xv[8], yg[8], yv[8]; unpack8(cgv, xg); unpack8(cvv, xv);
; #pragma unroll
;             for (int e = 0; e < 8; ++e) { yg[e] = bg[e] + wg[2][e] * xg[e]; yv[e] = bv[e] + wv[2][e] * xv[e]; }
; #pragma unroll
;             for (int d = 1; d <= 2; ++d) {
;                 const bool own = (rl + d <= 7); const int src = (lane + 64 - 8 * d) & 63;
;                 const u32x4 sg = own ? cgv : pg, sv = own ? cvv : pv;
;                 u32x4 g, v; g.x = __shfl(sg.x, src); g.y = __shfl(sg.y, src); g.z = __shfl(sg.z, src); g.w = __shfl(sg.w, src);
;                 v.x = __shfl(sv.x, src); v.y = __shfl(sv.y, src); v.z = __shfl(sv.z, src); v.w = __shfl(sv.w, src);
;                 float dg[8], dv[8]; unpack8(g, dg); unpack8(v, dv);
; #pragma unroll
;                 for (int e = 0; e < 8; ++e) { yg[e] += wg[2 - d][e] * dg[e]; yv[e] += wv[2 - d][e] * dv[e]; }
;             }
; #pragma unroll
;             for (int e = 0; e < 8; ++e) yg[e] = yg[e] * sigm(yg[e]) * yv[e];
;             { const u32x4 o_ = pack8(yg); if (st) *(u32x4*)(h1 + off) = o_; else asm volatile("" :: "v"(o_)); }
;             pg = cgv; pv = cvv;
	v_lshlrev_b32_e32 v84, 16, v142
	ds_bpermute_b32 v143, v147, v89
	v_pk_fma_f32 v[88:89], v[120:121], v[84:85], v[82:83]
	v_and_b32_e32 v83, 0xffff0000, v76
	v_and_b32_e32 v82, 0xffff0000, v80
	v_pk_fma_f32 v[82:83], v[18:19], v[82:83], v[26:27]
	v_and_b32_e32 v85, 0xffff0000, v99
	v_and_b32_e32 v84, 0xffff0000, v101
	v_pk_fma_f32 v[82:83], v[10:11], v[84:85], v[82:83]
	v_and_b32_e32 v85, 0xffff0000, v104
	v_and_b32_e32 v84, 0xffff0000, v142
	v_pk_fma_f32 v[86:87], v[2:3], v[84:85], v[82:83]
	v_lshlrev_b32_e32 v83, 16, v77
	v_lshlrev_b32_e32 v82, 16, v81
	v_pk_fma_f32 v[82:83], v[108:109], v[82:83], v[106:107]
	v_lshlrev_b32_e32 v85, 16, v100
	v_lshlrev_b32_e32 v84, 16, v102
	v_pk_fma_f32 v[82:83], v[110:111], v[84:85], v[82:83]
	v_lshlrev_b32_e32 v85, 16, v105
	s_waitcnt lgkmcnt(0)
	v_lshlrev_b32_e32 v84, 16, v143
	v_pk_fma_f32 v[84:85], v[112:113], v[84:85], v[82:83]
	v_and_b32_e32 v83, 0xffff0000, v77
	v_and_b32_e32 v82, 0xffff0000, v81
	v_pk_fma_f32 v[82:83], v[20:21], v[82:83], v[28:29]
	v_and_b32_e32 v99, 0xffff0000, v100
	v_and_b32_e32 v98, 0xffff0000, v102
	v_pk_fma_f32 v[82:83], v[12:13], v[98:99], v[82:83]
	v_and_b32_e32 v99, 0xffff0000, v105
	v_and_b32_e32 v98, 0xffff0000, v143
	v_pk_fma_f32 v[82:83], v[4:5], v[98:99], v[82:83]
	v_mul_f32_e32 v98, 0xbfb8aa3b, v95
	v_exp_f32_e32 v98, v98
	s_mov_b32 s9, 0x4a2c000
	v_add_f32_e32 v98, 1.0, v98
	s_nop 0
	v_rcp_f32_e32 v98, v98
	s_nop 0
	v_mul_f32_e32 v95, v95, v98
	v_mul_f32_e32 v94, v94, v95
	v_mul_f32_e32 v95, 0xbfb8aa3b, v97
	v_exp_f32_e32 v95, v95
	s_nop 0
	v_add_f32_e32 v95, 1.0, v95
	s_nop 0
	v_rcp_f32_e32 v95, v95
	s_nop 0
	v_mul_f32_e32 v95, v97, v95
	v_mul_f32_e32 v95, v96, v95
	v_mul_f32_e32 v96, 0xbfb8aa3b, v93
	v_exp_f32_e32 v96, v96
	s_nop 0
	v_add_f32_e32 v96, 1.0, v96
	s_nop 0
	v_rcp_f32_e32 v96, v96
	s_nop 0
	v_mul_f32_e32 v93, v93, v96
	v_mul_f32_e32 v92, v92, v93
	v_mul_f32_e32 v93, 0xbfb8aa3b, v91
	v_exp_f32_e32 v93, v93
	s_nop 0
	v_add_f32_e32 v93, 1.0, v93
	s_nop 0
	v_rcp_f32_e32 v93, v93
	s_nop 0
	v_mul_f32_e32 v91, v91, v93
	v_mul_f32_e32 v90, v90, v91
	v_mul_f32_e32 v91, 0xbfb8aa3b, v89
	v_exp_f32_e32 v91, v91
	s_nop 0
	v_add_f32_e32 v91, 1.0, v91
	s_nop 0
	v_rcp_f32_e32 v91, v91
	s_nop 0
	v_mul_f32_e32 v89, v89, v91
	v_mul_f32_e32 v88, v88, v89
	v_mul_f32_e32 v89, 0xbfb8aa3b, v87
	v_exp_f32_e32 v89, v89
	s_nop 0
	v_add_f32_e32 v89, 1.0, v89
	s_nop 0
	v_rcp_f32_e32 v89, v89
	s_nop 0
	v_mul_f32_e32 v87, v87, v89
	v_mul_f32_e32 v86, v86, v87
	v_mul_f32_e32 v87, 0xbfb8aa3b, v85
	v_exp_f32_e32 v87, v87
	s_nop 0
	v_add_f32_e32 v87, 1.0, v87
	s_nop 0
	v_rcp_f32_e32 v87, v87
	s_nop 0
	v_mul_f32_e32 v85, v85, v87
	v_mul_f32_e32 v85, v84, v85
	v_mul_f32_e32 v84, 0xbfb8aa3b, v83
	v_exp_f32_e32 v84, v84
	s_nop 0
	v_add_f32_e32 v84, 1.0, v84
	s_nop 0
	v_rcp_f32_e32 v84, v84
	s_nop 0
	v_mul_f32_e32 v83, v83, v84
	v_mul_f32_e32 v87, v82, v83
	v_cvt_pk_bf16_f32 v82, v94, v95
	v_cvt_pk_bf16_f32 v83, v92, v90
	v_cvt_pk_bf16_f32 v84, v88, v86
	v_add_co_u32_e32 v86, vcc, s9, v140
	v_cvt_pk_bf16_f32 v85, v85, v87
	s_waitcnt vmcnt(2)
	v_cndmask_b32_e64 v89, v70, v78, s[40:41]
	v_addc_co_u32_e32 v87, vcc, 0, v141, vcc
	global_store_dwordx4 v[86:87], v[82:85], off nt
	v_cndmask_b32_e64 v78, v78, v70, s[42:43]
	ds_bpermute_b32 v78, v147, v78
	v_cndmask_b32_e64 v82, v49, v77, s[40:41]
	v_cndmask_b32_e64 v85, v46, v74, s[40:41]
	v_cndmask_b32_e64 v83, v48, v76, s[40:41]
	ds_bpermute_b32 v94, v0, v85
	ds_bpermute_b32 v97, v0, v82
	ds_bpermute_b32 v82, v0, v89
	v_cndmask_b32_e64 v74, v74, v46, s[42:43]
	ds_bpermute_b32 v96, v0, v83
	ds_bpermute_b32 v83, v147, v74
	v_cndmask_b32_e64 v84, v47, v75, s[40:41]
	v_cndmask_b32_e64 v75, v75, v47, s[42:43]
	v_cndmask_b32_e64 v77, v77, v49, s[42:43]
	v_cndmask_b32_e64 v76, v76, v48, s[42:43]
	ds_bpermute_b32 v99, v147, v75
	v_lshlrev_b32_e32 v75, 16, v46
	v_lshlrev_b32_e32 v74, 16, v70
	v_cndmask_b32_e64 v88, v71, v79, s[40:41]
	ds_bpermute_b32 v100, v147, v76
	ds_bpermute_b32 v101, v147, v77
	v_pk_fma_f32 v[74:75], v[132:133], v[74:75], v[130:131]
	s_waitcnt lgkmcnt(7)
	v_lshlrev_b32_e32 v77, 16, v94
	s_waitcnt lgkmcnt(5)
	v_lshlrev_b32_e32 v76, 16, v82
	ds_bpermute_b32 v95, v0, v84
	ds_bpermute_b32 v88, v0, v88
	v_cndmask_b32_e64 v79, v79, v71, s[42:43]
	v_pk_fma_f32 v[74:75], v[134:135], v[76:77], v[74:75]
	s_waitcnt lgkmcnt(5)
	v_lshlrev_b32_e32 v77, 16, v83
	v_lshlrev_b32_e32 v76, 16, v78
	ds_bpermute_b32 v79, v147, v79
	v_pk_fma_f32 v[84:85], v[136:137], v[76:77], v[74:75]
	v_and_b32_e32 v75, 0xffff0000, v46
	v_and_b32_e32 v74, 0xffff0000, v70
	v_pk_fma_f32 v[74:75], v[22:23], v[74:75], v[30:31]
	v_and_b32_e32 v77, 0xffff0000, v94
	v_and_b32_e32 v76, 0xffff0000, v82
	v_cndmask_b32_e64 v86, v73, v81, s[40:41]
	v_cndmask_b32_e64 v87, v72, v80, s[40:41]
	v_pk_fma_f32 v[74:75], v[14:15], v[76:77], v[74:75]
	v_and_b32_e32 v77, 0xffff0000, v83
	v_and_b32_e32 v76, 0xffff0000, v78
	ds_bpermute_b32 v89, v0, v87
	ds_bpermute_b32 v98, v0, v86
	v_pk_fma_f32 v[86:87], v[6:7], v[76:77], v[74:75]
	v_lshlrev_b32_e32 v75, 16, v47
	v_lshlrev_b32_e32 v74, 16, v71
	v_pk_fma_f32 v[74:75], v[124:125], v[74:75], v[122:123]
	s_waitcnt lgkmcnt(4)
; __device__ __forceinline__ float sigm(float x) { return 1.f / (1.f + __expf(-x)); }
; __device__ __forceinline__ u32x4 pack8(const float (&f)[8]) { u32x4 w; w.x = pk2(f[0], f[1]); w.y = pk2(f[2], f[3]); w.z = pk2(f[4], f[5]); w.w = pk2(f[6], f[7]); return w; }
; __device__ __forceinline__ void ffn_conv_item(int tid_in, int b, int strip, bf16_t* h1, const bf16_t* h2, const float* cw, const float* cb, bool st = true) {
;     ...
;         for (int j = 0; j < 4; ++j) {
;             const size_t off = off0 + (size_t)(32 * blk + 8 * j + rl) * 5632;
;             const u32x4 cgv = cg4[j], cvv = cv4[j];
;             float xg[8], xv[8], yg[8], yv[8]; unpack8(cgv, xg); unpack8(cvv, xv);
; #pragma unroll
;             for (int e = 0; e < 8; ++e) { yg[e] = bg[e] + wg[2][e] * xg[e]; yv[e] = bv[e] + wv[2][e] * xv[e]; }
; #pragma unroll
;             for (int d = 1; d <= 2; ++d) {
;                 const bool own = (rl + d <= 7); const int src = (lane + 64 - 8 * d) & 63;
;                 const u32x4 sg = own ? cgv : pg, sv = own ? cvv : pv;
;                 u32x4 g, v; g.x = __shfl(sg.x, src); g.y = __shfl(sg.y, src); g.z = __shfl(sg.z, src); g.w = __shfl(sg.w, src);
;                 v.x = __shfl(sv.x, src); v.y = __shfl(sv.y, src); v.z = __shfl(sv.z, src); v.w = __shfl(sv.w, src);
;                 float dg[8], dv[8]; unpack8(g, dg); unpack8(v, dv);
; #pragma unroll
;                 for (int e = 0; e < 8; ++e) { yg[e] += wg[2 - d][e] * dg[e]; yv[e] += wv[2 - d][e] * dv[e]; }
;             }
; #pragma unroll
;             for (int e = 0; e < 8; ++e) yg[e] = yg[e] * sigm(yg[e]) * yv[e];
;             { const u32x4 o_ = pack8(yg); if (st) *(u32x4*)(h1 + off) = o_; else asm volatile("" :: "v"(o_)); }
;             pg = cgv; pv = cvv;
;         }
; #pragma unroll
;         for (int j = 0; j < 4; ++j) { cg4[j] = ng4[j]; cv4[j] = nv4[j]; }
	v_lshlrev_b32_e32 v77, 16, v95
	s_waitcnt lgkmcnt(3)
	v_lshlrev_b32_e32 v76, 16, v88
	v_cndmask_b32_e64 v80, v80, v72, s[42:43]
	v_pk_fma_f32 v[74:75], v[126:127], v[76:77], v[74:75]
	v_lshlrev_b32_e32 v77, 16, v99
	s_waitcnt lgkmcnt(2)
	v_lshlrev_b32_e32 v76, 16, v79
	v_mov_b64_e32 v[92:93], v[72:73]
	ds_bpermute_b32 v102, v147, v80
	v_pk_fma_f32 v[82:83], v[128:129], v[76:77], v[74:75]
	v_and_b32_e32 v75, 0xffff0000, v47
	v_and_b32_e32 v74, 0xffff0000, v71
	v_mov_b64_e32 v[90:91], v[70:71]
	v_pk_fma_f32 v[70:71], v[24:25], v[74:75], v[32:33]
	v_and_b32_e32 v75, 0xffff0000, v95
	v_and_b32_e32 v74, 0xffff0000, v88
	v_cndmask_b32_e64 v81, v81, v73, s[42:43]
	v_pk_fma_f32 v[70:71], v[16:17], v[74:75], v[70:71]
	v_and_b32_e32 v75, 0xffff0000, v99
	v_and_b32_e32 v74, 0xffff0000, v79
	ds_bpermute_b32 v103, v147, v81
	v_pk_fma_f32 v[80:81], v[8:9], v[74:75], v[70:71]
	v_lshlrev_b32_e32 v71, 16, v48
	v_lshlrev_b32_e32 v70, 16, v72
	v_pk_fma_f32 v[70:71], v[116:117], v[70:71], v[114:115]
	v_lshlrev_b32_e32 v75, 16, v96
	s_waitcnt lgkmcnt(3)
	v_lshlrev_b32_e32 v74, 16, v89
	v_pk_fma_f32 v[70:71], v[118:119], v[74:75], v[70:71]
	v_lshlrev_b32_e32 v75, 16, v100
	s_waitcnt lgkmcnt(1)
	v_lshlrev_b32_e32 v74, 16, v102
	v_pk_fma_f32 v[78:79], v[120:121], v[74:75], v[70:71]
	v_and_b32_e32 v71, 0xffff0000, v48
	v_and_b32_e32 v70, 0xffff0000, v72
	v_pk_fma_f32 v[70:71], v[18:19], v[70:71], v[26:27]
	v_and_b32_e32 v75, 0xffff0000, v96
	v_and_b32_e32 v74, 0xffff0000, v89
	v_pk_fma_f32 v[70:71], v[10:11], v[74:75], v[70:71]
	v_and_b32_e32 v75, 0xffff0000, v100
	v_and_b32_e32 v74, 0xffff0000, v102
	v_pk_fma_f32 v[76:77], v[2:3], v[74:75], v[70:71]
	v_lshlrev_b32_e32 v71, 16, v49
	v_lshlrev_b32_e32 v70, 16, v73
	v_pk_fma_f32 v[70:71], v[108:109], v[70:71], v[106:107]
	v_lshlrev_b32_e32 v75, 16, v97
	v_lshlrev_b32_e32 v74, 16, v98
	v_pk_fma_f32 v[70:71], v[110:111], v[74:75], v[70:71]
	v_lshlrev_b32_e32 v75, 16, v101
	s_waitcnt lgkmcnt(0)
	v_lshlrev_b32_e32 v74, 16, v103
	v_pk_fma_f32 v[74:75], v[112:113], v[74:75], v[70:71]
	v_and_b32_e32 v71, 0xffff0000, v49
	v_and_b32_e32 v70, 0xffff0000, v73
	v_pk_fma_f32 v[70:71], v[20:21], v[70:71], v[28:29]
	v_and_b32_e32 v73, 0xffff0000, v97
	v_and_b32_e32 v72, 0xffff0000, v98
	v_pk_fma_f32 v[70:71], v[12:13], v[72:73], v[70:71]
	v_and_b32_e32 v73, 0xffff0000, v101
	v_and_b32_e32 v72, 0xffff0000, v103
	v_pk_fma_f32 v[70:71], v[4:5], v[72:73], v[70:71]
	v_mul_f32_e32 v72, 0xbfb8aa3b, v85
	v_exp_f32_e32 v72, v72
	v_mov_b64_e32 v[100:101], v[44:45]
	v_mov_b64_e32 v[104:105], v[48:49]
	v_mov_b64_e32 v[98:99], v[42:43]
	v_add_f32_e32 v72, 1.0, v72
	v_mov_b64_e32 v[102:103], v[46:47]
	v_rcp_f32_e32 v72, v72
	s_nop 0
	v_mul_f32_e32 v73, 0xbfb8aa3b, v87
	v_exp_f32_e32 v73, v73
	v_mul_f32_e32 v72, v85, v72
	v_mul_f32_e32 v72, v84, v72
	v_add_f32_e32 v73, 1.0, v73
	s_nop 0
	v_rcp_f32_e32 v73, v73
	s_nop 0
	v_mul_f32_e32 v84, 0xbfb8aa3b, v83
	v_exp_f32_e32 v84, v84
	v_mul_f32_e32 v73, v87, v73
	v_mul_f32_e32 v73, v86, v73
	v_mov_b64_e32 v[96:97], v[40:41]
	v_add_f32_e32 v84, 1.0, v84
	v_mov_b64_e32 v[94:95], v[38:39]
	v_rcp_f32_e32 v84, v84
	s_nop 0
	v_mul_f32_e32 v83, v83, v84
	v_mul_f32_e32 v82, v82, v83
	v_mul_f32_e32 v83, 0xbfb8aa3b, v81
	v_exp_f32_e32 v83, v83
	s_nop 0
	v_add_f32_e32 v83, 1.0, v83
	s_nop 0
	v_rcp_f32_e32 v83, v83
	s_nop 0
	v_mul_f32_e32 v81, v81, v83
	v_mul_f32_e32 v80, v80, v81
	v_mul_f32_e32 v81, 0xbfb8aa3b, v79
	v_exp_f32_e32 v81, v81
	s_nop 0
	v_add_f32_e32 v81, 1.0, v81
	s_nop 0
	v_rcp_f32_e32 v81, v81
	s_nop 0
	v_mul_f32_e32 v79, v79, v81
	v_mul_f32_e32 v78, v78, v79
	v_mul_f32_e32 v79, 0xbfb8aa3b, v77
	v_exp_f32_e32 v79, v79
	s_nop 0
	v_add_f32_e32 v79, 1.0, v79
	s_nop 0
	v_rcp_f32_e32 v79, v79
	s_nop 0
	v_mul_f32_e32 v77, v77, v79
	v_mul_f32_e32 v76, v76, v77
	v_mul_f32_e32 v77, 0xbfb8aa3b, v75
	v_exp_f32_e32 v77, v77
	v_mov_b64_e32 v[88:89], v[56:57]
	v_mov_b64_e32 v[86:87], v[54:55]
	v_add_f32_e32 v77, 1.0, v77
	s_nop 0
	v_rcp_f32_e32 v77, v77
	s_nop 0
	v_mul_f32_e32 v75, v75, v77
	v_mul_f32_e32 v74, v74, v75
	v_mul_f32_e32 v75, 0xbfb8aa3b, v71
	v_exp_f32_e32 v75, v75
	s_nop 0
	v_add_f32_e32 v75, 1.0, v75
	s_nop 0
	v_rcp_f32_e32 v75, v75
	s_nop 0
	v_mul_f32_e32 v71, v71, v75
	v_mul_f32_e32 v75, v70, v71
	v_cvt_pk_bf16_f32 v70, v72, v73
	v_cvt_pk_bf16_f32 v71, v82, v80
	v_cvt_pk_bf16_f32 v72, v78, v76
	v_cvt_pk_bf16_f32 v73, v74, v75
	v_add_co_u32_e32 v74, vcc, 0x4a42000, v140
	v_mov_b64_e32 v[84:85], v[52:53]
	s_nop 0
	v_addc_co_u32_e32 v75, vcc, 0, v141, vcc
	global_store_dwordx4 v[74:75], v[70:73], off nt
	v_mov_b64_e32 v[76:77], v[60:61]
	v_mov_b64_e32 v[80:81], v[64:65]
	v_mov_b64_e32 v[72:73], v[68:69]
	v_mov_b64_e32 v[74:75], v[58:59]
	v_mov_b64_e32 v[82:83], v[50:51]
	v_mov_b64_e32 v[70:71], v[66:67]
	v_mov_b64_e32 v[78:79], v[62:63]
	s_cbranch_scc0 .LBB0_17
